# fast path v15 = v14 + biased K/V prefetch pointers with +-2048 immediates (13 -> 9 address instructions) and pairwise-merged staging vmcnt waits
# speedup vs baseline: 1.0111x; 1.0014x over previous
; #define MFMA32(a, b, c) __builtin_amdgcn_mfma_f32_32x32x16_bf16((a), (b), (c), 0, 0, 0)
; DI unsigned pk_bf16(float lo, float hi) { f32x2 v = {lo, hi}; bf16v2 b = __builtin_convertvector(v, bf16v2); return __builtin_bit_cast(unsigned, b); }
; DI int crow(int r, int h) { return (r & 3) + 8 * (r >> 2) + 4 * h; }
; DI void attn_item(const Params& p, int g, int seq, int hd, int qt, int m, char* smem, int split_j, int sub) {
;     ...
;     bf16x8 kf[4], vf[2][4];
; #pragma unroll
;     for (int s = 0; s < 4; ++s) kf[s] = *(const bf16x8*)(Kb + l31 * 72 + s * 16 + h * 8);
; #pragma unroll
;     for (int s2 = 0; s2 < 2; ++s2)
; #pragma unroll
;       for (int dt = 0; dt < 4; ++dt) vf[s2][dt] = *(const bf16x8*)(Vb + (dt * 32 + l31) * 40 + s2 * 16 + h * 8);
;     __builtin_amdgcn_sched_barrier(0);
;     f32x16 X;
; #pragma unroll
;     for (int r = 0; r < 16; ++r) X[r] = 0.f;
; #pragma unroll
;     for (int s = 0; s < 4; ++s) X = MFMA32(kf[s], qf[s], X);
;     if (farL || farR) {
; #pragma unroll
;       for (int r = 0; r < 16; ++r) X[r] = __builtin_amdgcn_exp2f(X[r]);
;     } else {
;       const int rel0 = k0 - (qw0 + l31) + 128;
; #pragma unroll
;       for (int r = 0; r < 16; ++r) { int idx = rel0 + crow(r, h); idx = idx < 0 ? 0 : (idx > 256 ? 256 : idx); X[r] = __builtin_amdgcn_exp2f(X[r] + tab[idx]); }
;     }
;     bf16x8 pf[2];
; #pragma unroll
;     for (int s2 = 0; s2 < 2; ++s2) {
;       u32x4 w; w.x = pk_bf16(X[8 * s2], X[8 * s2 + 1]); w.y = pk_bf16(X[8 * s2 + 2], X[8 * s2 + 3]); w.z = pk_bf16(X[8 * s2 + 4], X[8 * s2 + 5]); w.w = pk_bf16(X[8 * s2 + 6], X[8 * s2 + 7]);
;       ls2 += (f32x2){X[8 * s2], X[8 * s2 + 1]}; ls2 += (f32x2){X[8 * s2 + 2], X[8 * s2 + 3]};
;       ls2 += (f32x2){X[8 * s2 + 4], X[8 * s2 + 5]}; ls2 += (f32x2){X[8 * s2 + 6], X[8 * s2 + 7]};
;       pf[s2] = __builtin_bit_cast(bf16x8, w);
;     }
; #pragma unroll
;     for (int s2 = 0; s2 < 2; ++s2)
; #pragma unroll
;       for (int dt = 0; dt < 4; ++dt) O[dt] = MFMA32(pf[s2], vf[s2][dt], O[dt]);
.Lat2_reads:
	ds_read_b128 v[64:67], v192
	ds_read_b128 v[80:83], v192 offset:32
	ds_read_b128 v[84:87], v192 offset:64
	ds_read_b128 v[88:91], v192 offset:96
	s_waitcnt lgkmcnt(3)
	v_mfma_f32_32x32x16_bf16 v[64:79], v[64:67], v[104:107], 0
	ds_read_b128 v[220:223], v192 offset:4608
	ds_read_b128 v[224:227], v192 offset:4640
	ds_read_b128 v[236:239], v192 offset:4672
	ds_read_b128 v[240:243], v192 offset:4704
	s_waitcnt lgkmcnt(6)
	v_mfma_f32_32x32x16_bf16 v[64:79], v[80:83], v[108:111], v[64:79]
	ds_read_b128 v[156:159], v244 offset:18432
	ds_read_b128 v[160:163], v244 offset:20992
	s_waitcnt lgkmcnt(7)
	v_mfma_f32_32x32x16_bf16 v[64:79], v[84:87], v[112:115], v[64:79]
	ds_read_b128 v[164:167], v244 offset:23552
	ds_read_b128 v[152:155], v244 offset:26112
	s_waitcnt lgkmcnt(8)
	v_mfma_f32_32x32x16_bf16 v[64:79], v[88:91], v[116:119], v[64:79]
	ds_read_b128 v[148:151], v244 offset:18464
	ds_read_b128 v[144:147], v244 offset:21024
	ds_read_b128 v[136:139], v244 offset:23584
	ds_read_b128 v[140:143], v244 offset:26144
	s_waitcnt lgkmcnt(8)
	v_mfma_f32_32x32x16_bf16 v[80:95], v[220:223], v[104:107], 0
	v_mfma_f32_32x32x16_bf16 v[80:95], v[224:227], v[108:111], v[80:95]
	v_exp_f32_e32 v64, v64
	v_exp_f32_e32 v65, v65
	v_exp_f32_e32 v66, v66
	v_exp_f32_e32 v67, v67
	v_exp_f32_e32 v68, v68
	v_exp_f32_e32 v69, v69
	v_mfma_f32_32x32x16_bf16 v[80:95], v[236:239], v[112:115], v[80:95]
	v_exp_f32_e32 v70, v70
	v_exp_f32_e32 v71, v71
	v_exp_f32_e32 v72, v72
	v_exp_f32_e32 v73, v73
	v_exp_f32_e32 v74, v74
	v_exp_f32_e32 v75, v75
	v_mfma_f32_32x32x16_bf16 v[80:95], v[240:243], v[116:119], v[80:95]
	v_exp_f32_e32 v76, v76
	v_exp_f32_e32 v77, v77
	v_exp_f32_e32 v78, v78
	v_exp_f32_e32 v79, v79
	v_cvt_pk_bf16_f32 v220, v64, v65
	v_cvt_pk_bf16_f32 v221, v66, v67
	v_cvt_pk_bf16_f32 v222, v68, v69
	v_cvt_pk_bf16_f32 v223, v70, v71
	v_cvt_pk_bf16_f32 v224, v72, v73
	v_cvt_pk_bf16_f32 v225, v74, v75
	v_cvt_pk_bf16_f32 v226, v76, v77
	v_cvt_pk_bf16_f32 v227, v78, v79
	s_waitcnt lgkmcnt(0)
	v_mfma_f32_32x32x16_bf16 v[48:63], v[220:223], v[156:159], v[48:63]
	ds_read_b128 v[156:159], v244 offset:28672
	v_exp_f32_e32 v80, v80
	v_exp_f32_e32 v81, v81
	v_exp_f32_e32 v82, v82
	v_mfma_f32_32x32x16_bf16 v[32:47], v[220:223], v[160:163], v[32:47]
	ds_read_b128 v[160:163], v244 offset:31232
	v_exp_f32_e32 v83, v83
	v_exp_f32_e32 v84, v84
	v_exp_f32_e32 v85, v85
	v_mfma_f32_32x32x16_bf16 v[16:31], v[220:223], v[164:167], v[16:31]
	ds_read_b128 v[164:167], v244 offset:33792
	v_exp_f32_e32 v86, v86
	v_exp_f32_e32 v87, v87
	v_exp_f32_e32 v88, v88
	v_mfma_f32_32x32x16_bf16 v[0:15], v[220:223], v[152:155], v[0:15]
	ds_read_b128 v[152:155], v244 offset:36352
	v_exp_f32_e32 v89, v89
	v_exp_f32_e32 v90, v90
	v_exp_f32_e32 v91, v91
	v_mfma_f32_32x32x16_bf16 v[48:63], v[224:227], v[148:151], v[48:63]
	ds_read_b128 v[148:151], v244 offset:28704
	v_exp_f32_e32 v92, v92
	v_exp_f32_e32 v93, v93
	v_exp_f32_e32 v94, v94
	v_exp_f32_e32 v95, v95
	v_mfma_f32_32x32x16_bf16 v[32:47], v[224:227], v[144:147], v[32:47]
	ds_read_b128 v[144:147], v244 offset:31264
	v_cvt_pk_bf16_f32 v236, v80, v81
	v_cvt_pk_bf16_f32 v237, v82, v83
	v_cvt_pk_bf16_f32 v238, v84, v85
	v_add_f32_e32 v246, v66, v70
	v_add_f32_e32 v247, v67, v71
	v_add_f32_e32 v186, v186, v64
	v_add_f32_e32 v187, v187, v65
	v_mfma_f32_32x32x16_bf16 v[16:31], v[224:227], v[136:139], v[16:31]
	ds_read_b128 v[136:139], v244 offset:33824
	v_cvt_pk_bf16_f32 v239, v86, v87
	v_cvt_pk_bf16_f32 v240, v88, v89
	v_cvt_pk_bf16_f32 v241, v90, v91
	v_add_f32_e32 v246, v246, v74
	v_add_f32_e32 v247, v247, v75
	v_add_f32_e32 v186, v186, v68
	v_add_f32_e32 v187, v187, v69
	v_mfma_f32_32x32x16_bf16 v[0:15], v[224:227], v[140:143], v[0:15]
	ds_read_b128 v[140:143], v244 offset:36384
	v_cvt_pk_bf16_f32 v242, v92, v93
	v_cvt_pk_bf16_f32 v243, v94, v95
	v_add_f32_e32 v246, v246, v78
	v_add_f32_e32 v247, v247, v79
	v_add_f32_e32 v186, v186, v72
	v_add_f32_e32 v187, v187, v73
	s_andn2_b64 vcc, exec, s[8:9]
	s_cbranch_vccnz .Lat2_pvplain
; DI void attn_item(const Params& p, int g, int seq, int hd, int qt, int m, char* smem, int split_j, int sub) {
;     ...
;   auto load_tile = [&](int t, u32x4& k, u32x4& v0, u32x4& v1) __attribute__((always_inline)) {
;     k = *(const u32x4*)(ksrc + (size_t)(tbase + t) * 2048);
;     v0 = *(const u32x4*)(vsrc + (size_t)(tbase + t) * 4096); v1 = *(const u32x4*)(vsrc + (size_t)(tbase + t) * 4096 + 2048);
;   };
;   auto store_tile = [&](int buf, const u32x4& k, const u32x4& v0, const u32x4& v1) __attribute__((always_inline)) {
;     bf16_t* Kn = Ks + buf * 32 * 72; bf16_t* Vn = Vs + buf * 128 * 40;
;     *(u32x4*)(Kn + kr0 * 72 + kc) = k;
;     *(u32x4*)(Vn + vr0 * 40 + vc) = v0; *(u32x4*)(Vn + (vr0 + 64) * 40 + vc) = v1;
;   };
;     ...
;   for (int it = 0; it < npairs; ++it) {
;     const int set = it & 1;
;     if (it + 1 < npairs) { load_tile(2 * it + 2, rkA, rvA0, rvA1); load_tile(2 * it + 3, rkB, rvB0, rvB1); }
;     compute(2 * it, 2 * set);
;     compute(2 * it + 1, 2 * set + 1);
;     if (it + 1 < npairs) { store_tile(2 * (set ^ 1), rkA, rvA0, rvA1); store_tile(2 * (set ^ 1) + 1, rkB, rvB0, rvB1); }
	s_add_i32 s10, s15, 1
	s_cmp_lt_u32 s10, s73
	s_cbranch_scc0 .Lat2_pvw
	s_xor_b32 s7, s16, 2
	s_mul_i32 s8, s7, 0x2800
	s_add_i32 s8, s8, 32
	s_mulk_i32 s7, 0x1200
	v_add_u32_e32 v192, s7, v169
	v_add3_u32 v244, s8, v189, v190
	s_addk_i32 s8, 0x2800
	s_add_i32 s13, s13, 64
	s_add_i32 s6, s6, 2
	s_mov_b32 s15, s10
	s_mov_b64 s[20:21], 0x2000
	s_waitcnt lgkmcnt(6)
	v_mfma_f32_32x32x16_bf16 v[48:63], v[236:239], v[156:159], v[48:63]
	s_waitcnt vmcnt(4)
	ds_write_b128 v192, v[96:99]
	s_add_i32 s50, s6, -1
	s_lshl_b64 s[10:11], s[50:51], 12
	s_add_u32 s10, s10, 0x800
	v_lshl_add_u64 v[220:221], v[172:173], 0, s[10:11]
	v_add_f32_e32 v186, v186, v76
	v_add_f32_e32 v187, v187, v77
	v_mfma_f32_32x32x16_bf16 v[32:47], v[236:239], v[160:163], v[32:47]
	ds_write_b128 v244, v[100:103] offset:18432
	global_load_dwordx4 v[96:99], v[220:221], off offset:-2048
	s_lshl_b64 s[10:11], s[50:51], 13
	s_add_u32 s10, s10, 0x800
	v_lshl_add_u64 v[222:223], v[170:171], 0, s[10:11]
	v_add_f32_e32 v186, v186, v246
	v_add_f32_e32 v187, v187, v247
	s_waitcnt lgkmcnt(6)
	v_mfma_f32_32x32x16_bf16 v[16:31], v[236:239], v[164:167], v[16:31]
	s_waitcnt vmcnt(3)
	ds_write_b128 v244, v[120:123] offset:23552
	global_load_dwordx4 v[100:103], v[222:223], off offset:-2048
	v_lshl_add_u64 v[224:225], v[222:223], 0, s[20:21]
	v_add_f32_e32 v246, v82, v86
	v_add_f32_e32 v247, v83, v87
	v_add_f32_e32 v186, v186, v80
	v_mfma_f32_32x32x16_bf16 v[0:15], v[236:239], v[152:155], v[0:15]
	ds_write_b128 v192, v[124:127] offset:4608
	global_load_dwordx4 v[120:123], v[222:223], off offset:2048
	v_add_f32_e32 v187, v187, v81
	v_add_f32_e32 v246, v246, v90
	v_add_f32_e32 v247, v247, v91
	s_waitcnt lgkmcnt(6)
	v_mfma_f32_32x32x16_bf16 v[48:63], v[240:243], v[148:151], v[48:63]
	v_add3_u32 v192, s8, v189, v190
	s_waitcnt vmcnt(3)
	ds_write_b128 v192, v[128:131] offset:18432
	global_load_dwordx4 v[124:127], v[220:221], off offset:2048
	v_add_f32_e32 v186, v186, v84
	v_add_f32_e32 v187, v187, v85
	v_add_f32_e32 v246, v246, v94
	v_mfma_f32_32x32x16_bf16 v[32:47], v[240:243], v[144:147], v[32:47]
	ds_write_b128 v192, v[132:135] offset:23552
	global_load_dwordx4 v[128:131], v[224:225], off offset:-2048
	v_add_f32_e32 v247, v247, v95
	v_add_f32_e32 v186, v186, v88
	v_add_f32_e32 v187, v187, v89
	s_waitcnt lgkmcnt(6)
	v_mfma_f32_32x32x16_bf16 v[16:31], v[240:243], v[136:139], v[16:31]
	global_load_dwordx4 v[132:135], v[224:225], off offset:2048
	v_add_f32_e32 v186, v186, v92
	v_add_f32_e32 v187, v187, v93
	s_add_i32 s7, s14, s13
	s_cmpk_lt_i32 s7, 0xff42
	s_cselect_b32 s19, 1, 0
	s_cmpk_gt_i32 s7, 0x9e
	s_cselect_b32 s50, 1, 0
	s_cmp_eq_u32 s17, 2
	s_cselect_b32 s50, s50, 0
	s_or_b32 s19, s19, s50
	v_mfma_f32_32x32x16_bf16 v[0:15], v[240:243], v[140:143], v[0:15]
	v_add_f32_e32 v186, v186, v246
	v_add_f32_e32 v187, v187, v247
	s_mov_b64 s[8:9], -1
	s_add_i32 s10, s6, -3
	s_and_b32 s16, s10, 2
	s_mul_i32 s10, s16, 0x1200
	s_mul_i32 s18, s16, 0x2800
	v_add_u32_e32 v192, s10, v191
	v_add_u32_e32 v244, s18, v196
	s_cmp_lg_u32 s19, 0
	s_waitcnt lgkmcnt(0)
	s_barrier
	s_cbranch_scc1 .Lat2_reads
	s_branch .LBB0_319
